# thr: fourth sweep skips tiles via per-tile candidate lists, skip decided at loop top before waiting on the prefetched key fragments
# baseline (speedup 1.0000x reference)
; DI void dsa_thr_item(const Params& p, int b, int qblk, char* smem) {
;     ...
;     for (int kt = wave; kt <= qblk; kt += 8) {
;       const bf16x8 k0 = kn0, k1 = kn1;
;       {
;         const int ktn = min(kt + 8, qblk);
;         kn0 = ldg8(kib + (size_t)ktn * 1024); kn1 = ldg8(kib + (size_t)ktn * 1024 + 512);
;       }
.LBB0_268:
	s_add_i32 s99, s99, 1
	v_mov_b32_e32 v97, v96
	v_add_u32_e32 v96, 8, v97
	v_min_i32_e32 v52, s71, v96
	v_lshlrev_b64 v[0:1], 11, v[52:53]
	s_cmp_eq_u32 s72, 3
	s_cbranch_scc0 .Lthr_noskip
	v_readfirstlane_b32 s100, v97
	s_cmp_eq_u32 s100, s71
	s_cbranch_scc1 .Lthr_noskip
	s_mul_i32 s100, s99, 0x140
	v_lshlrev_b32_e32 v10, 10, v167
	v_lshl_add_u32 v10, v10, 2, v10
	v_add_u32_e32 v10, 0x10800, v10
	v_add_u32_e32 v10, s100, v10
	v_lshl_add_u32 v11, v177, 2, v10
	ds_read_b32 v12, v10
	ds_read_b32 v13, v11 offset:4
	s_waitcnt lgkmcnt(0)
	v_readfirstlane_b32 s100, v12
	s_cmp_gt_u32 s100, 64
	s_cbranch_scc1 .Lthr_noskip
	v_and_b32_e32 v14, 0x7c, v13
	ds_read_b32 v14, v14 offset:32768
	v_lshrrev_b32_e32 v15, 7, v13
	v_cmp_gt_u32_e64 s[6:7], s100, v177
	s_waitcnt lgkmcnt(0)
	v_and_b32_e32 v14, 0xff, v14
	v_cmp_eq_u32_e64 s[8:9], v14, v15
	s_and_b64 s[6:7], s[6:7], s[8:9]
	s_cmp_lg_u64 s[6:7], 0
	s_cbranch_scc1 .Lthr_noskip
	v_lshl_add_u64 v[0:1], v[54:55], 0, v[0:1]
	global_load_dwordx4 v[32:35], v[0:1], off
	global_load_dwordx4 v[36:39], v[0:1], off offset:1024
	s_mov_b64 s[0:1], exec
	s_branch .LBB0_267
; #define MFMA(a, b, c) __builtin_amdgcn_mfma_f32_32x32x16_bf16((a), (b), (c), 0, 0, 0)
; DI f32x16 zero16() { f32x16 z; for (int i = 0; i < 16; ++i) z[i] = 0.f; return z; }
; DI void dsa_thr_item(const Params& p, int b, int qblk, char* smem) {
;     ...
;     for (int kt = wave; kt <= qblk; kt += 8) {
;       const bf16x8 k0 = kn0, k1 = kn1;
;       {
;         const int ktn = min(kt + 8, qblk);
;         kn0 = ldg8(kib + (size_t)ktn * 1024); kn1 = ldg8(kib + (size_t)ktn * 1024 + 512);
;       }
;       float sc[16];
;       {
;         f32x16 a = zero16();
;         a = MFMA(k0, *reinterpret_cast<const bf16x8*>(qil + 256), a);
;         a = MFMA(k1, *reinterpret_cast<const bf16x8*>(qil + 256 + 16), a);
; #pragma unroll
;         for (int i = 0; i < 16; ++i) sc[i] = a[i];
;       }
; #pragma unroll
;       for (int hd = 0; hd < 8; ++hd) {
;         f32x16 a = zero16();
;         a = MFMA(k0, *reinterpret_cast<const bf16x8*>(qil + hd * 32), a);
;         a = MFMA(k1, *reinterpret_cast<const bf16x8*>(qil + hd * 32 + 16), a);
;         const float wh = wq[hd];
; #pragma unroll
;         for (int i = 0; i < 16; ++i) sc[i] = fmaf(fabsf(a[i]), wh, sc[i]);
;       }
.Lthr_noskip:
	s_waitcnt vmcnt(0)
	v_mov_b64_e32 v[42:43], v[38:39]
	s_waitcnt vmcnt(0)
	v_mov_b64_e32 v[46:47], v[34:35]
	v_lshl_add_u64 v[0:1], v[54:55], 0, v[0:1]
	v_mov_b64_e32 v[40:41], v[36:37]
	v_mov_b64_e32 v[44:45], v[32:33]
	global_load_dwordx4 v[32:35], v[0:1], off
	global_load_dwordx4 v[36:39], v[0:1], off offset:1024
	v_mfma_f32_32x32x16_bf16 v[104:119], v[44:47], v[184:187], 0
	v_mfma_f32_32x32x16_bf16 v[104:119], v[40:43], v[188:191], v[104:119]
	v_cmp_ne_u32_e64 s[0:1], s71, v97
	s_mov_b64 s[62:63], 0
	v_mfma_f32_32x32x16_bf16 v[120:135], v[44:47], v[192:195], 0
	v_mfma_f32_32x32x16_bf16 v[120:135], v[40:43], v[196:199], v[120:135]
	v_mfma_f32_32x32x16_bf16 v[136:151], v[44:47], v[200:203], 0
	v_mfma_f32_32x32x16_bf16 v[136:151], v[40:43], v[220:223], v[136:151]
	s_nop 9
	v_fma_f32 v152, |v120|, v79, v104
	v_fma_f32 v153, |v121|, v79, v105
	v_fma_f32 v154, |v122|, v79, v106
	v_fma_f32 v155, |v123|, v79, v107
	v_fma_f32 v156, |v124|, v79, v108
	v_fma_f32 v157, |v125|, v79, v109
	v_fma_f32 v158, |v126|, v79, v110
	v_fma_f32 v159, |v127|, v79, v111
	v_fma_f32 v160, |v128|, v79, v112
	v_fma_f32 v161, |v129|, v79, v113
	v_fma_f32 v98, |v130|, v79, v114
	v_fma_f32 v99, |v131|, v79, v115
	v_fma_f32 v100, |v132|, v79, v116
	v_fma_f32 v101, |v133|, v79, v117
	v_fma_f32 v102, |v134|, v79, v118
	v_fma_f32 v103, |v135|, v79, v119
	v_mfma_f32_32x32x16_bf16 v[104:119], v[44:47], v[224:227], 0
	v_mfma_f32_32x32x16_bf16 v[104:119], v[40:43], v[228:231], v[104:119]
	v_fma_f32 v152, |v136|, v80, v152
	v_fma_f32 v153, |v137|, v80, v153
	v_fma_f32 v154, |v138|, v80, v154
	v_fma_f32 v155, |v139|, v80, v155
	v_fma_f32 v156, |v140|, v80, v156
	v_fma_f32 v157, |v141|, v80, v157
	v_fma_f32 v158, |v142|, v80, v158
	v_fma_f32 v159, |v143|, v80, v159
	v_fma_f32 v160, |v144|, v80, v160
	v_fma_f32 v161, |v145|, v80, v161
	v_fma_f32 v98, |v146|, v80, v98
	v_fma_f32 v99, |v147|, v80, v99
	v_fma_f32 v100, |v148|, v80, v100
	v_fma_f32 v101, |v149|, v80, v101
	v_fma_f32 v102, |v150|, v80, v102
	v_fma_f32 v103, |v151|, v80, v103
	v_mfma_f32_32x32x16_bf16 v[120:135], v[44:47], v[232:235], 0
	v_mfma_f32_32x32x16_bf16 v[120:135], v[40:43], v[236:239], v[120:135]
	v_fma_f32 v152, |v104|, v81, v152
	v_fma_f32 v153, |v105|, v81, v153
	v_fma_f32 v154, |v106|, v81, v154
	v_fma_f32 v155, |v107|, v81, v155
	v_fma_f32 v156, |v108|, v81, v156
	v_fma_f32 v157, |v109|, v81, v157
	v_fma_f32 v158, |v110|, v81, v158
	v_fma_f32 v159, |v111|, v81, v159
	v_fma_f32 v160, |v112|, v81, v160
	v_fma_f32 v161, |v113|, v81, v161
	v_fma_f32 v98, |v114|, v81, v98
	v_fma_f32 v99, |v115|, v81, v99
	v_fma_f32 v100, |v116|, v81, v100
	v_fma_f32 v101, |v117|, v81, v101
	v_fma_f32 v102, |v118|, v81, v102
	v_fma_f32 v103, |v119|, v81, v103
	v_mfma_f32_32x32x16_bf16 v[136:151], v[44:47], v[240:243], 0
	v_mfma_f32_32x32x16_bf16 v[136:151], v[40:43], v[244:247], v[136:151]
	ds_read_b128 v[4:7], v216 offset:33632
	v_fma_f32 v152, |v120|, v82, v152
	v_fma_f32 v153, |v121|, v82, v153
	v_fma_f32 v154, |v122|, v82, v154
	v_fma_f32 v155, |v123|, v82, v155
	v_fma_f32 v156, |v124|, v82, v156
	v_fma_f32 v157, |v125|, v82, v157
	v_fma_f32 v158, |v126|, v82, v158
	v_fma_f32 v159, |v127|, v82, v159
	v_fma_f32 v160, |v128|, v82, v160
	v_fma_f32 v161, |v129|, v82, v161
	v_fma_f32 v98, |v130|, v82, v98
	v_fma_f32 v99, |v131|, v82, v99
	v_fma_f32 v100, |v132|, v82, v100
	v_fma_f32 v101, |v133|, v82, v101
	v_fma_f32 v102, |v134|, v82, v102
	v_fma_f32 v103, |v135|, v82, v103
	s_waitcnt lgkmcnt(0)
	v_mfma_f32_32x32x16_bf16 v[104:119], v[44:47], v[248:251], 0
	v_mfma_f32_32x32x16_bf16 v[104:119], v[40:43], v[4:7], v[104:119]
	ds_read_b128 v[8:11], v216 offset:33664
	ds_read_b128 v[12:15], v216 offset:33696
	v_fma_f32 v152, |v136|, v83, v152
	v_fma_f32 v153, |v137|, v83, v153
	v_fma_f32 v154, |v138|, v83, v154
	v_fma_f32 v155, |v139|, v83, v155
	v_fma_f32 v156, |v140|, v83, v156
	v_fma_f32 v157, |v141|, v83, v157
	v_fma_f32 v158, |v142|, v83, v158
	v_fma_f32 v159, |v143|, v83, v159
	v_fma_f32 v160, |v144|, v83, v160
	v_fma_f32 v161, |v145|, v83, v161
	v_fma_f32 v98, |v146|, v83, v98
	v_fma_f32 v99, |v147|, v83, v99
	v_fma_f32 v100, |v148|, v83, v100
	v_fma_f32 v101, |v149|, v83, v101
	v_fma_f32 v102, |v150|, v83, v102
	v_fma_f32 v103, |v151|, v83, v103
	s_waitcnt lgkmcnt(0)
	v_mfma_f32_32x32x16_bf16 v[120:135], v[44:47], v[8:11], 0
	v_mfma_f32_32x32x16_bf16 v[120:135], v[40:43], v[12:15], v[120:135]
	ds_read_b128 v[0:3], v216 offset:33728
	ds_read_b128 v[4:7], v216 offset:33760
	v_fma_f32 v152, |v104|, v84, v152
	v_fma_f32 v153, |v105|, v84, v153
	v_fma_f32 v154, |v106|, v84, v154
	v_fma_f32 v155, |v107|, v84, v155
	v_fma_f32 v156, |v108|, v84, v156
	v_fma_f32 v157, |v109|, v84, v157
	v_fma_f32 v158, |v110|, v84, v158
	v_fma_f32 v159, |v111|, v84, v159
	v_fma_f32 v160, |v112|, v84, v160
	v_fma_f32 v161, |v113|, v84, v161
	v_fma_f32 v98, |v114|, v84, v98
	v_fma_f32 v99, |v115|, v84, v99
	v_fma_f32 v100, |v116|, v84, v100
	v_fma_f32 v101, |v117|, v84, v101
	v_fma_f32 v102, |v118|, v84, v102
	v_fma_f32 v103, |v119|, v84, v103
	s_waitcnt lgkmcnt(0)
	v_mfma_f32_32x32x16_bf16 v[136:151], v[44:47], v[0:3], 0
	v_mfma_f32_32x32x16_bf16 v[136:151], v[40:43], v[4:7], v[136:151]
	v_fma_f32 v152, |v120|, v85, v152
	v_fma_f32 v153, |v121|, v85, v153
	v_fma_f32 v154, |v122|, v85, v154
	v_fma_f32 v155, |v123|, v85, v155
	v_fma_f32 v156, |v124|, v85, v156
	v_fma_f32 v157, |v125|, v85, v157
	v_fma_f32 v158, |v126|, v85, v158
	v_fma_f32 v159, |v127|, v85, v159
	v_fma_f32 v160, |v128|, v85, v160
	v_fma_f32 v161, |v129|, v85, v161
	v_fma_f32 v98, |v130|, v85, v98
	v_fma_f32 v99, |v131|, v85, v99
	v_fma_f32 v100, |v132|, v85, v100
	v_fma_f32 v101, |v133|, v85, v101
	v_fma_f32 v102, |v134|, v85, v102
	v_fma_f32 v103, |v135|, v85, v103
	v_fma_f32 v40, |v136|, v86, v152
	v_fma_f32 v22, |v137|, v86, v153
	v_fma_f32 v21, |v138|, v86, v154
	v_fma_f32 v20, |v139|, v86, v155
	v_fma_f32 v19, |v140|, v86, v156
	v_fma_f32 v18, |v141|, v86, v157
	v_fma_f32 v17, |v142|, v86, v158
	v_fma_f32 v16, |v143|, v86, v159
	v_fma_f32 v7, |v144|, v86, v160
	v_fma_f32 v6, |v145|, v86, v161
	v_fma_f32 v5, |v146|, v86, v98
	v_fma_f32 v4, |v147|, v86, v99
	v_fma_f32 v3, |v148|, v86, v100
	v_fma_f32 v2, |v149|, v86, v101
	v_fma_f32 v1, |v150|, v86, v102
	v_fma_f32 v0, |v151|, v86, v103
	v_ashrrev_i32_e32 v8, 31, v40
	v_bitop3_b32 v8, v8, v40, s67 bitop3:0x36
	v_lshrrev_b32_e32 v9, s58, v8
	v_lshrrev_b32_e32 v8, 8, v9
	v_cmp_eq_u32_e64 s[52:53], v8, v94
	s_and_saveexec_b64 s[64:65], s[0:1]
	s_xor_b64 s[64:65], exec, s[64:65]
	s_cbranch_execnz .LBB0_271
	s_andn2_saveexec_b64 s[64:65], s[64:65]
	s_cbranch_execnz .LBB0_302
